# v31 plus next-layer weight conversion split: w_in phase converts 2 items per wave, the rest at the gate_up phase start on the CUs with one tile fewer
# speedup vs baseline: 1.0294x; 1.0183x over previous
; __device__ __forceinline__ ArgsP args_ptr() { ArgsP p = (ArgsP)__builtin_amdgcn_kernarg_segment_ptr(); asm volatile("" : "+s"(p)); return p; }
; __device__ __forceinline__ void convert_layer(ArgsP a, int L, int first, int stride, int lane) {
;     unsigned char* ws = a->ws;
;     bf16* WIN = (bf16*)(ws + WS_WIN); bf16* WOUT = (bf16*)(ws + WS_WOUT); bf16* WGU = (bf16*)(ws + WS_WGU); bf16* WDN = (bf16*)(ws + WS_WDN);
;     for (int r = first; r < I_L; r += stride) {
;         if (r < I_IN) transpose_item(a->in[3] + (size_t)L * D * INW, D, INW, WIN + (size_t)L * INW * D, a->in[2] + L * D, 1, 0, r, lane);
;         else if (r < I_IN + I_OUT) transpose_item(a->in[4] + (size_t)L * D * D, D, D, WOUT + (size_t)L * D * D, nullptr, 0, 0, r - I_IN, lane);
;         else if (r < I_IN + I_OUT + I_GU) transpose_item(a->in[18] + (size_t)L * D * GU, D, GU, WGU + (size_t)L * GU * D, a->in[17] + L * D, 2, 0, r - I_IN - I_OUT, lane);
;         else transpose_item(a->in[19] + (size_t)L * FFN * D, FFN, D, WDN + (size_t)L * D * FFN, nullptr, 0, 0, r - I_IN - I_OUT - I_GU, lane);
;     }
; }
; __device__ __forceinline__ void phase_A(unsigned char* lds, int wave_s, int L) {
;     ...
;     if (L + 1 < DEPTH && bx >= 128 && bx < 224) { convert_layer(args_ptr(), L + 1, (bx - 128) * NWAVES + wave, 96 * NWAVES, lane); asm volatile("s_waitcnt vmcnt(0)" ::: "memory"); }
.LBB0_88:
	s_add_i32 s4, s1, 0x300
	s_addk_i32 s26, 0x6000
	s_addk_i32 s27, 0xc00
	s_add_i32 s3, s3, 0xc000
	v_add_u32_e32 v82, 0xc000, v82
	s_cmpk_lt_i32 s1, 0x300
	s_mov_b32 s1, s4
	global_store_dwordx4 v[78:79], v[0:3], off offset:112
	s_cbranch_scc0 .LBB0_108

; __device__ __forceinline__ ArgsP args_ptr() { ArgsP p = (ArgsP)__builtin_amdgcn_kernarg_segment_ptr(); asm volatile("" : "+s"(p)); return p; }
; #define TIDS() int lane_ = (int)__builtin_amdgcn_mbcnt_hi(~0u, __builtin_amdgcn_mbcnt_lo(~0u, 0u)); asm volatile("" : "+v"(lane_)); const int lane = lane_ & 63, wave = wave_s & 7, tid = wave * 64 + lane; const int G = gridDim.x, bx = blockIdx.x; (void)lane; (void)wave; (void)tid; (void)G; (void)bx
; __device__ __forceinline__ void convert_layer(ArgsP a, int L, int first, int stride, int lane) {
;     unsigned char* ws = a->ws;
;     bf16* WIN = (bf16*)(ws + WS_WIN); bf16* WOUT = (bf16*)(ws + WS_WOUT); bf16* WGU = (bf16*)(ws + WS_WGU); bf16* WDN = (bf16*)(ws + WS_WDN);
;     for (int r = first; r < I_L; r += stride) {
;         if (r < I_IN) transpose_item(a->in[3] + (size_t)L * D * INW, D, INW, WIN + (size_t)L * INW * D, a->in[2] + L * D, 1, 0, r, lane);
;         else if (r < I_IN + I_OUT) transpose_item(a->in[4] + (size_t)L * D * D, D, D, WOUT + (size_t)L * D * D, nullptr, 0, 0, r - I_IN, lane);
;         else if (r < I_IN + I_OUT + I_GU) transpose_item(a->in[18] + (size_t)L * D * GU, D, GU, WGU + (size_t)L * GU * D, a->in[17] + L * D, 2, 0, r - I_IN - I_OUT, lane);
;         else transpose_item(a->in[19] + (size_t)L * FFN * D, FFN, D, WDN + (size_t)L * D * FFN, nullptr, 0, 0, r - I_IN - I_OUT - I_GU, lane);
;     }
; }
; __device__ __forceinline__ void phase_D(unsigned char* lds, int wave_s, int L) {
;     ArgsP a = args_ptr(); TIDS(); unsigned char* ws = a->ws;
;     pg8::Gemm g{(bf16*)(ws + WS_XB), (bf16*)(ws + WS_WGU) + (size_t)L * GU * D, M, GU, D}; pg8::StaticOrder S; S.init(M, GU, G, bx);
;     pg8::EpiSwi E{(bf16*)(ws + WS_ACT), (const float*)(ws + WS_SS)};
;     pg8::gemm_phase<pg8::EpiSwi, pg8::StaticOrder, true, true>((pg8::PG8_LAS_T*)lds, g, S, E, tid);
.LBB0_511:
	s_or_b64 exec, exec, s[10:11]
	s_mov_b64 s[10:11], s[96:97]
	s_waitcnt lgkmcnt(0)
	v_mov_b32_e32 v0, v201
	v_readlane_b32 s1, v252, 5
	s_barrier
	s_cmp_lt_u32 s2, 0x80
	s_cbranch_scc1 .Lcsc0_skip
	v_mov_b32_e32 v128, v0
	v_mov_b32_e32 v129, v2
	v_mov_b32_e32 v130, v3
	v_mov_b32_e32 v131, v64
	v_mov_b32_e32 v132, v65
	v_mov_b32_e32 v133, v66
	v_mov_b32_e32 v134, v67
	v_mov_b32_e32 v135, v68
	v_mov_b32_e32 v136, v69
	v_mov_b32_e32 v137, v70
	v_mov_b32_e32 v138, v71
	v_mov_b32_e32 v139, v72
	v_mov_b32_e32 v140, v73
	v_mov_b32_e32 v141, v74
	v_mov_b32_e32 v142, v75
	v_mov_b32_e32 v143, v76
	v_mov_b32_e32 v144, v77
	v_mov_b32_e32 v145, v78
	v_mov_b32_e32 v146, v79
	v_mov_b32_e32 v147, v81
	v_mov_b32_e32 v148, v82
	v_mov_b32_e32 v149, v83
	v_mov_b32_e32 v150, v84
	v_mov_b32_e32 v151, v85
	v_mov_b32_e32 v152, v86
	v_mov_b32_e32 v153, v87
	v_mov_b32_e32 v154, v88
	v_mov_b32_e32 v155, v89
	v_mov_b32_e32 v156, v90
	v_mov_b32_e32 v157, v91
	v_writelane_b32 v253, s1, 0
	v_writelane_b32 v253, s6, 1
	v_writelane_b32 v253, s7, 2
	v_writelane_b32 v253, s16, 3
	v_writelane_b32 v253, s34, 4
	v_writelane_b32 v253, s35, 5
	v_writelane_b32 v253, s36, 6
	v_writelane_b32 v253, s38, 7
	v_writelane_b32 v253, s39, 8
	v_writelane_b32 v253, s44, 9
	v_writelane_b32 v253, s46, 10
	v_writelane_b32 v253, s59, 11
	v_writelane_b32 v253, s60, 12
	v_writelane_b32 v253, s61, 13
	v_writelane_b32 v253, s70, 14
	v_writelane_b32 v253, s71, 15
	v_writelane_b32 v253, s72, 16
	v_writelane_b32 v253, s86, 17
	v_writelane_b32 v253, s87, 18
	v_and_b32_e32 v80, 63, v201
	s_mov_b64 s[12:13], s[96:97]
	s_load_dwordx2 s[4:5], s[12:13], 0xa8
	v_readlane_b32 s1, v252, 2
	v_readlane_b32 s14, v252, 1
	s_nop 3
	s_add_i32 s1, s1, s14
	s_add_i32 s1, s1, 0x200
	v_lshlrev_b32_e32 v0, 2, v80
	s_waitcnt lgkmcnt(0)
	s_add_u32 s14, s4, 0x4e80000
	s_addc_u32 s15, s5, 0
	s_add_u32 s16, s4, 0x2800000
	s_addc_u32 s17, s5, 0
	s_add_u32 s18, s4, 0x1700000
	s_addc_u32 s19, s5, 0
	s_add_u32 s22, s4, 0x600000
	s_addc_u32 s23, s5, 0
	s_lshl_b32 s3, s1, 6
	v_and_b32_e32 v81, 0x80, v0
	v_or_b32_e32 v82, s3, v80
	s_lshl_b32 s26, s1, 5
	s_lshl_b32 s27, s1, 2
	v_mov_b32_e32 v13, 0
	s_movk_i32 s30, 0x7fff
	s_mov_b32 s31, 0xffff0000
	v_mov_b32_e32 v83, 0x1000
	v_mov_b32_e32 v84, 1
	s_mov_b32 s33, 0xa0f000
	s_mov_b32 s34, 0xa11000
	s_mov_b32 s35, 0xa14000
	s_mov_b32 s36, 0xa16000
	s_mov_b32 s37, 0xa19000
	s_mov_b32 s38, 0xa1b000
	s_mov_b32 s39, 0xa1e000
	s_mov_b32 s40, 0xa20000
	s_mov_b32 s41, 0xa23000
	s_mov_b32 s42, 0xa25000
	s_mov_b32 s43, 0xa28000
	s_mov_b32 s44, 0xa2a000
	s_mov_b32 s45, 0xa2d000
	s_mov_b32 s46, 0xa2f000
	s_mov_b32 s47, 0xa32000
	s_mov_b32 s48, 0xa34000
	s_mov_b32 s49, 0xa37000
	s_mov_b32 s50, 0xa39000
	s_mov_b32 s51, 0xa3c000
	s_mov_b32 s52, 0xa3e000
	s_mov_b32 s53, 0xa41000
	s_mov_b32 s54, 0xa43000
	s_mov_b32 s55, 0xa46000
	s_mov_b32 s56, 0xa48000
	s_mov_b32 s57, 0xa4b000
	s_mov_b32 s58, 0xa4d000
	s_mov_b32 s59, 0xa50000
	s_mov_b32 s60, 0xa52000
	s_mov_b32 s61, 0xa55000
	s_mov_b32 s62, 0xa57000
	s_mov_b32 s63, 0xa5a000
	s_mov_b32 s64, 0xa5c000
	s_mov_b32 s65, 0xa5f000
	s_mov_b32 s66, 0xa61000
	s_mov_b32 s67, 0xa64000
	s_mov_b32 s68, 0xa66000
	s_mov_b32 s69, 0xa69000
	s_mov_b32 s70, 0xa6b000
	s_mov_b32 s71, 0xa6e000
	s_mov_b32 s72, 0xa70000
	s_mov_b32 s73, 0xa73000
	s_mov_b32 s74, 0xa75000
	s_mov_b32 s75, 0xa78000
	s_mov_b32 s76, 0xa7a000
	s_mov_b32 s77, 0xa7d000
	s_mov_b32 s78, 0xa7f000
	s_mov_b32 s79, 0xa82000
	s_mov_b32 s80, 0xa84000
	s_mov_b32 s81, 0xa87000
	s_mov_b32 s82, 0xa89000
	s_mov_b32 s83, 0xa8c000
	s_mov_b32 s84, 0xa8e000
	s_mov_b32 s85, 0xa91000
	s_mov_b32 s86, 0xa93000
	s_mov_b32 s87, 0xa96000
	s_mov_b32 s88, 0xa98000
	s_mov_b32 s89, 0xa9b000
	s_mov_b32 s90, 0xa9d000
	s_mov_b32 s25, 0
	s_branch .Lcsc0_89

; __device__ __forceinline__ unsigned pk2(float lo, float hi) { return f2bf(lo) | (f2bf(hi) << 16); }
; __device__ __forceinline__ void transpose_item(const float* __restrict__ W, int K, int N, bf16* __restrict__ WT, const float* __restrict__ ksc, int mode, int row_off, int item, int lane) {
;     const int nblk = N / 64, kb = item / nblk, nb = item % nblk, k0 = 64 * kb, n = 64 * nb + lane;
;     const float* src = W + (size_t)k0 * N + n;
;     float v[64];
; #pragma unroll
;     for (int i = 0; i < 64; ++i) v[i] = __builtin_nontemporal_load(src + (size_t)i * N);
;     if (ksc) {
; #pragma unroll
;         for (int i = 0; i < 64; ++i) v[i] *= ksc[k0 + i];
;     }
;     bf16* dst = WT + (size_t)(row_off + map_row(n, mode)) * K + k0;
; #pragma unroll
;     for (int j = 0; j < 8; ++j) { v4u o; o.x = pk2(v[8 * j], v[8 * j + 1]); o.y = pk2(v[8 * j + 2], v[8 * j + 3]); o.z = pk2(v[8 * j + 4], v[8 * j + 5]); o.w = pk2(v[8 * j + 6], v[8 * j + 7]);
;         *(v4u*)(dst + 8 * j) = o; }
; __device__ __forceinline__ void convert_layer(ArgsP a, int L, int first, int stride, int lane) {
;     ...
;     for (int r = first; r < I_L; r += stride) {
;         if (r < I_IN) transpose_item(a->in[3] + (size_t)L * D * INW, D, INW, WIN + (size_t)L * INW * D, a->in[2] + L * D, 1, 0, r, lane);
;         else if (r < I_IN + I_OUT) transpose_item(a->in[4] + (size_t)L * D * D, D, D, WOUT + (size_t)L * D * D, nullptr, 0, 0, r - I_IN, lane);
;         else if (r < I_IN + I_OUT + I_GU) transpose_item(a->in[18] + (size_t)L * D * GU, D, GU, WGU + (size_t)L * GU * D, a->in[17] + L * D, 2, 0, r - I_IN - I_OUT, lane);
;         else transpose_item(a->in[19] + (size_t)L * FFN * D, FFN, D, WDN + (size_t)L * D * FFN, nullptr, 0, 0, r - I_IN - I_OUT - I_GU, lane);
;     }
.Lcsc0_88:
	s_add_i32 s4, s1, 0x400
	s_add_i32 s26, s26, 0x8000
	s_addk_i32 s27, 0x1000
	s_add_i32 s3, s3, 0x10000
	v_add_u32_e32 v82, 0x10000, v82
	s_cmpk_lt_i32 s1, 0x7c0
	s_mov_b32 s1, s4
	global_store_dwordx4 v[78:79], v[0:3], off offset:112
	s_cbranch_scc0 .Lcsc0_108

; #define PG8_LAS __attribute__((address_space(3)))
; #define PG8_WAIT_V(n) asm volatile("s_waitcnt vmcnt(" #n ")" ::: "memory")
; template <class Epi, class Sched, bool ALIGN_EPI = false, bool SP2 = false>
; __device__ __forceinline__ void gemm_phase(PG8_LAS unsigned char* lds, const Gemm g, const Sched& S, const Epi& E, int tid_in) {
;     int tid_ = tid_in; asm volatile("" : "+v"(tid_));
;     const int tid = tid_, wid = __builtin_amdgcn_readfirstlane(tid >> 6), lane = tid & 63, wr = wid >> 2, wc = wid & 3, fr = lane & 15, fq = lane >> 4;
;     const int K = g.K, nt = K / BK;
;     unsigned voffA[2], voffB[2];
; #pragma unroll
;     for (int i = 0; i < 2; ++i) { int R, C; stage_rc(tid * 16 + i * 8192, R, C); const int Rb = Epi::PERM ? ((R & ~31) + perm32(R & 31)) : R;
;         voffA[i] = (unsigned)(R * K + C) * 2u; voffB[i] = (unsigned)(Rb * K + C) * 2u; }
;     const size_t kstep = (size_t)(BK * 2);
;     const size_t hstep = (size_t)HALF * K * 2;
;     const size_t tstep = 2 * hstep;
;     const unsigned ldsw = (unsigned)wid * 1024u;
;     const int aoff = lds_byte(wr * 64 + fr, fq * 8), boff = lds_byte(wc * 32 + fr, fq * 8);
;     ...
;     Unit cur, nxt; int ui = 0;
;     if (!S.next(0, cur)) return;
;     f32x4 acc[2][2][4][2];
; #pragma unroll
;     for (int a = 0; a < 2; ++a)
; #pragma unroll
;         for (int b = 0; b < 2; ++b)
; #pragma unroll
;             for (int m = 0; m < 4; ++m)
; #pragma unroll
;                 for (int n = 0; n < 2; ++n) acc[a][b][m][n] = (f32x4){0.f, 0.f, 0.f, 0.f};
;     bf16x8 At[4][2], B0[2][2], B1[2][2];
;     const char* cA = (const char*)g.A + (size_t)cur.pm * tstep; const char* cB = (const char*)g.Bt + (size_t)cur.pn * tstep;
;     S.a_ready(cur);
;     if constexpr (SP2) {
;         PG8_STAGE(PG8_SB(0, 0), cB, voffB); PG8_STAGE(PG8_SB(0, 1), cB + hstep, voffB); PG8_STAGE(PG8_SA(0, 0), cA, voffA); PG8_STAGE(PG8_SA(0, 1), cA + hstep, voffA);
;         if (wr == 1) PG8_BAR;
;         PG8_WAIT_V(2); PG8_BAR;
;         PG8_STAGE(PG8_SB(1, 0), cB + kstep, voffB); PG8_STAGE(PG8_SA(1, 0), cA + kstep, voffA); PG8_STAGE(PG8_SB(1, 1), cB + hstep + kstep, voffB);
;         PG8_WAIT_V(6); PG8_BAR;
;     } else {
;         PG8_STAGE(PG8_SB(0, 0), cB, voffB); PG8_STAGE(PG8_SA(0, 0), cA, voffA); PG8_STAGE(PG8_SB(0, 1), cB + hstep, voffB); PG8_STAGE(PG8_SA(0, 1), cA + hstep, voffA);
;         if (wr == 1) PG8_BAR;
.Lcsc0_108:
	s_waitcnt vmcnt(0)
	v_mov_b32_e32 v0, v128
	v_mov_b32_e32 v2, v129
	v_mov_b32_e32 v3, v130
	v_mov_b32_e32 v64, v131
	v_mov_b32_e32 v65, v132
	v_mov_b32_e32 v66, v133
	v_mov_b32_e32 v67, v134
	v_mov_b32_e32 v68, v135
	v_mov_b32_e32 v69, v136
	v_mov_b32_e32 v70, v137
	v_mov_b32_e32 v71, v138
	v_mov_b32_e32 v72, v139
	v_mov_b32_e32 v73, v140
	v_mov_b32_e32 v74, v141
	v_mov_b32_e32 v75, v142
	v_mov_b32_e32 v76, v143
	v_mov_b32_e32 v77, v144
	v_mov_b32_e32 v78, v145
	v_mov_b32_e32 v79, v146
	v_mov_b32_e32 v81, v147
	v_mov_b32_e32 v82, v148
	v_mov_b32_e32 v83, v149
	v_mov_b32_e32 v84, v150
	v_mov_b32_e32 v85, v151
	v_mov_b32_e32 v86, v152
	v_mov_b32_e32 v87, v153
	v_mov_b32_e32 v88, v154
	v_mov_b32_e32 v89, v155
	v_mov_b32_e32 v90, v156
	v_mov_b32_e32 v91, v157
	v_readlane_b32 s1, v253, 0
	v_readlane_b32 s6, v253, 1
	v_readlane_b32 s7, v253, 2
	v_readlane_b32 s16, v253, 3
	v_readlane_b32 s34, v253, 4
	v_readlane_b32 s35, v253, 5
	v_readlane_b32 s36, v253, 6
	v_readlane_b32 s38, v253, 7
	v_readlane_b32 s39, v253, 8
	v_readlane_b32 s44, v253, 9
	v_readlane_b32 s46, v253, 10
	v_readlane_b32 s59, v253, 11
	v_readlane_b32 s60, v253, 12
	v_readlane_b32 s61, v253, 13
	v_readlane_b32 s70, v253, 14
	v_readlane_b32 s71, v253, 15
	v_readlane_b32 s72, v253, 16
	v_readlane_b32 s86, v253, 17
	v_readlane_b32 s87, v253, 18
	s_nop 4
.Lcsc0_skip:
	s_cmpk_lt_i32 s2, 0x580
	v_and_or_b32 v8, v0, 63, s1
	s_cselect_b64 s[42:43], -1, 0
	s_cmpk_gt_i32 s2, 0x57f
	v_readfirstlane_b32 s19, v8
	s_cbranch_scc1 .LBB0_527
	v_lshlrev_b32_e32 v0, 4, v8
	v_add_u32_e32 v1, 0x2000, v0
	v_ashrrev_i32_e32 v2, 31, v1
	v_lshrrev_b32_e32 v2, 22, v2
	v_add_u32_e32 v2, v1, v2
	v_ashrrev_i32_e32 v9, 10, v2
	v_mul_i32_i24_e32 v2, 0x400, v9
	v_sub_u32_e32 v1, v1, v2
	v_lshrrev_b32_e32 v2, 4, v1
	v_bitop3_b32 v1, v2, v1, 32 bitop3:0x6c
	v_ashrrev_i32_e32 v2, 31, v1
	v_lshrrev_b32_e32 v2, 26, v2
	v_add_u32_e32 v2, v1, v2
	v_lshlrev_b32_e32 v3, 3, v9
	v_ashrrev_i32_e32 v10, 6, v2
	v_and_b32_e32 v3, -16, v3
	v_add_u32_e32 v3, v10, v3
	v_and_b32_e32 v4, 3, v10
	s_mov_b32 s12, 0x1fffe0
	v_lshrrev_b32_e32 v5, 2, v3
	v_lshlrev_b32_e32 v6, 1, v3
	v_and_b32_e32 v2, 0xc0, v2
	v_and_or_b32 v4, v3, s12, v4
	v_and_b32_e32 v5, 4, v5
	v_and_b32_e32 v6, 24, v6
	v_sub_u32_e32 v1, v1, v2
	v_mov_b32_e32 v2, 1
	v_or3_b32 v4, v4, v5, v6
	v_lshlrev_b32_e32 v5, 5, v9
	v_ashrrev_i16_sdwa v1, v2, sext(v1) dst_sel:DWORD dst_unused:UNUSED_PAD src0_sel:DWORD src1_sel:BYTE_0
	v_and_b32_e32 v5, 32, v5
	v_bfe_i32 v11, v1, 0, 16
	v_add_lshl_u32 v1, v5, v11, 1
	v_lshl_add_u32 v128, v4, 11, v1
	v_lshl_add_u32 v130, v3, 11, v1
	v_bfe_i32 v1, v8, 27, 1
	v_lshrrev_b32_e32 v1, 22, v1
	v_add_u32_e32 v1, v0, v1
	s_load_dwordx2 s[10:11], s[10:11], 0xa8
	v_and_b32_e32 v1, 0xfffffc00, v1
	v_sub_u32_e32 v0, v0, v1
	v_lshrrev_b32_e32 v1, 4, v0
	v_ashrrev_i32_e32 v3, 31, v8
	v_bitop3_b32 v0, v1, v0, 32 bitop3:0x6c
	v_lshrrev_b32_e32 v3, 26, v3
	v_ashrrev_i32_e32 v1, 31, v0
	v_add_u32_e32 v3, v8, v3
	s_waitcnt lgkmcnt(0)
	s_add_u32 s1, s10, 0x6900000
	v_lshrrev_b32_e32 v1, 26, v1
	v_ashrrev_i32_e32 v13, 6, v3
	s_addc_u32 s3, s11, 0
	v_add_u32_e32 v1, v0, v1
	v_lshlrev_b32_e32 v3, 3, v13
	s_add_u32 s4, s10, 0x1d00000
	v_ashrrev_i32_e32 v12, 6, v1
	v_and_b32_e32 v3, -16, v3
	s_addc_u32 s5, s11, 0
	v_add_u32_e32 v3, v12, v3
	v_and_b32_e32 v4, 3, v12
	s_ashr_i32 s31, s2, 31
	v_and_or_b32 v4, v3, s12, v4
	s_lshr_b32 s12, s31, 29
	s_add_i32 s12, s2, s12
	s_ashr_i32 s16, s19, 6
	s_ashr_i32 s13, s12, 3
	s_and_b32 s12, s12, -8
	s_ashr_i32 s22, s19, 8
	s_lshl_b32 s30, s16, 10
	s_sub_i32 s12, s2, s12
	s_cmp_lt_i32 s12, 0
	s_movk_i32 s33, 0xb1
	s_cselect_b32 s14, s33, 0xb0
	s_mul_i32 s12, s14, s12
	s_add_i32 s12, s12, s13
	s_mul_hi_i32 s13, s12, 0x2e8ba2e9
	s_lshr_b32 s14, s13, 31
	s_ashr_i32 s13, s13, 5
	s_add_i32 s13, s13, s14
	s_lshl_b32 s14, s13, 3
	s_mulk_i32 s13, 0xb0
	s_sub_i32 s12, s12, s13
	s_sext_i32_i16 s13, s12
	s_bfe_u32 s13, s13, 0x3001c
	s_add_i32 s13, s12, s13
	s_sext_i32_i16 s15, s13
	s_and_b32 s13, s13, 0xfff8
	s_sub_i32 s12, s12, s13
	s_sext_i32_i16 s12, s12
	v_lshrrev_b32_e32 v5, 2, v3
	v_lshlrev_b32_e32 v6, 1, v3
	v_and_b32_e32 v1, 0xc0, v1
	s_lshr_b32 s18, s15, 3
	s_add_i32 s36, s14, s12
	v_and_b32_e32 v5, 4, v5
	v_and_b32_e32 v6, 24, v6
	v_sub_u32_e32 v0, v0, v1
	s_ashr_i32 s37, s36, 31
	s_bfe_i64 s[14:15], s[18:19], 0x100000
	v_or3_b32 v4, v4, v5, v6
	v_lshlrev_b32_e32 v5, 5, v13
	v_ashrrev_i16_sdwa v0, v2, sext(v0) dst_sel:DWORD dst_unused:UNUSED_PAD src0_sel:DWORD src1_sel:BYTE_0
	s_lshl_b64 s[12:13], s[36:37], 19
	s_lshl_b64 s[14:15], s[14:15], 19
	v_and_b32_e32 v5, 32, v5
	v_bfe_i32 v14, v0, 0, 16
	s_add_u32 s38, s4, s14
	v_add_lshl_u32 v0, v5, v14, 1
	s_addc_u32 s39, s5, s15
	s_add_i32 s37, s30, 0
	v_lshl_add_u32 v132, v4, 11, v0
	s_add_i32 m0, s37, 0x10000
	v_lshl_add_u32 v134, v3, 11, v0
	global_load_lds_dwordx4 v132, s[38:39]
	s_add_i32 m0, s37, 0x12000
	s_add_u32 s14, s38, 0x40000
	global_load_lds_dwordx4 v128, s[38:39]
	s_addc_u32 s15, s39, 0
	s_add_i32 m0, s37, 0x14000
	v_mov_b32_e32 v133, 0
	global_load_lds_dwordx4 v132, s[14:15]
	s_add_i32 m0, s37, 0x16000
	s_add_u32 s40, s1, s12
	s_addc_u32 s41, s3, s13
	s_add_i32 s46, s37, 0x2000
	global_load_lds_dwordx4 v128, s[14:15]
	s_mov_b32 m0, s37
	s_add_u32 s12, s40, 0x40000
	global_load_lds_dwordx4 v134, s[40:41]
	s_mov_b32 m0, s46
	s_addc_u32 s13, s41, 0
	s_add_i32 s47, s37, 0x4000
	global_load_lds_dwordx4 v130, s[40:41]
	s_mov_b32 m0, s47
	s_add_i32 s48, s37, 0x6000
	global_load_lds_dwordx4 v134, s[12:13]
	s_mov_b32 m0, s48
	v_mov_b32_e32 v129, v133
	global_load_lds_dwordx4 v130, s[12:13]
	v_mov_b32_e32 v135, v133
	v_mov_b32_e32 v131, v133
	s_cmp_eq_u32 s22, 1
	s_mov_b32 s49, 0
	v_lshl_add_u64 v[6:7], s[38:39], 0, v[132:133]
	v_lshl_add_u64 v[4:5], s[38:39], 0, v[128:129]
	v_lshl_add_u64 v[0:1], s[40:41], 0, v[134:135]
	s_cselect_b64 s[12:13], -1, 0
	s_cmp_lg_u32 s22, 1
	v_lshl_add_u64 v[2:3], s[40:41], 0, v[130:131]
	s_cbranch_scc1 .LBB0_514
	s_barrier

; __device__ __forceinline__ ArgsP args_ptr() { ArgsP p = (ArgsP)__builtin_amdgcn_kernarg_segment_ptr(); asm volatile("" : "+s"(p)); return p; }
; __device__ __forceinline__ void convert_layer(ArgsP a, int L, int first, int stride, int lane) {
;     ...
;     for (int r = first; r < I_L; r += stride) {
;         if (r < I_IN) transpose_item(a->in[3] + (size_t)L * D * INW, D, INW, WIN + (size_t)L * INW * D, a->in[2] + L * D, 1, 0, r, lane);
;         else if (r < I_IN + I_OUT) transpose_item(a->in[4] + (size_t)L * D * D, D, D, WOUT + (size_t)L * D * D, nullptr, 0, 0, r - I_IN, lane);
;         else if (r < I_IN + I_OUT + I_GU) transpose_item(a->in[18] + (size_t)L * D * GU, D, GU, WGU + (size_t)L * GU * D, a->in[17] + L * D, 2, 0, r - I_IN - I_OUT, lane);
;         else transpose_item(a->in[19] + (size_t)L * FFN * D, FFN, D, WDN + (size_t)L * D * FFN, nullptr, 0, 0, r - I_IN - I_OUT - I_GU, lane);
;     }
; __device__ __forceinline__ void phase_A(unsigned char* lds, int wave_s, int L) {
;     ...
;     if (L + 1 < DEPTH && bx >= 128 && bx < 224) { convert_layer(args_ptr(), L + 1, (bx - 128) * NWAVES + wave, 96 * NWAVES, lane); asm volatile("s_waitcnt vmcnt(0)" ::: "memory"); }
.LBB0_680:
	s_add_i32 s14, s1, 0x300
	s_addk_i32 s4, 0x6000
	s_addk_i32 s5, 0xc00
	s_add_i32 s3, s3, 0xc000
	v_add_u32_e32 v82, 0xc000, v82
	s_cmpk_lt_i32 s1, 0x300
	s_mov_b32 s1, s14
	global_store_dwordx4 v[78:79], v[0:3], off offset:112
	s_cbranch_scc0 .LBB0_700

; __device__ __forceinline__ ArgsP args_ptr() { ArgsP p = (ArgsP)__builtin_amdgcn_kernarg_segment_ptr(); asm volatile("" : "+s"(p)); return p; }
; #define TIDS() int lane_ = (int)__builtin_amdgcn_mbcnt_hi(~0u, __builtin_amdgcn_mbcnt_lo(~0u, 0u)); asm volatile("" : "+v"(lane_)); const int lane = lane_ & 63, wave = wave_s & 7, tid = wave * 64 + lane; const int G = gridDim.x, bx = blockIdx.x; (void)lane; (void)wave; (void)tid; (void)G; (void)bx
; __device__ __forceinline__ void convert_layer(ArgsP a, int L, int first, int stride, int lane) {
;     unsigned char* ws = a->ws;
;     bf16* WIN = (bf16*)(ws + WS_WIN); bf16* WOUT = (bf16*)(ws + WS_WOUT); bf16* WGU = (bf16*)(ws + WS_WGU); bf16* WDN = (bf16*)(ws + WS_WDN);
;     for (int r = first; r < I_L; r += stride) {
;         if (r < I_IN) transpose_item(a->in[3] + (size_t)L * D * INW, D, INW, WIN + (size_t)L * INW * D, a->in[2] + L * D, 1, 0, r, lane);
;         else if (r < I_IN + I_OUT) transpose_item(a->in[4] + (size_t)L * D * D, D, D, WOUT + (size_t)L * D * D, nullptr, 0, 0, r - I_IN, lane);
;         else if (r < I_IN + I_OUT + I_GU) transpose_item(a->in[18] + (size_t)L * D * GU, D, GU, WGU + (size_t)L * GU * D, a->in[17] + L * D, 2, 0, r - I_IN - I_OUT, lane);
;         else transpose_item(a->in[19] + (size_t)L * FFN * D, FFN, D, WDN + (size_t)L * D * FFN, nullptr, 0, 0, r - I_IN - I_OUT - I_GU, lane);
;     }
; }
; __device__ __forceinline__ void phase_D(unsigned char* lds, int wave_s, int L) {
;     ArgsP a = args_ptr(); TIDS(); unsigned char* ws = a->ws;
;     pg8::Gemm g{(bf16*)(ws + WS_XB), (bf16*)(ws + WS_WGU) + (size_t)L * GU * D, M, GU, D}; pg8::StaticOrder S; S.init(M, GU, G, bx);
;     pg8::EpiSwi E{(bf16*)(ws + WS_ACT), (const float*)(ws + WS_SS)};
;     pg8::gemm_phase<pg8::EpiSwi, pg8::StaticOrder, true, true>((pg8::PG8_LAS_T*)lds, g, S, E, tid);
.LBB0_987:
	s_or_b64 exec, exec, s[12:13]
	v_readlane_b32 s16, v252, 15
	v_readlane_b32 s17, v252, 16
	s_waitcnt lgkmcnt(0)
	v_mov_b32_e32 v0, v201
	s_barrier
	s_cmp_lt_u32 s2, 0x80
	s_cbranch_scc1 .Lcsc1_skip
	v_mov_b32_e32 v128, v0
	v_mov_b32_e32 v129, v1
	v_mov_b32_e32 v130, v2
	v_mov_b32_e32 v131, v3
	v_mov_b32_e32 v132, v64
	v_mov_b32_e32 v133, v65
	v_mov_b32_e32 v134, v66
	v_mov_b32_e32 v135, v67
	v_mov_b32_e32 v136, v68
	v_mov_b32_e32 v137, v69
	v_mov_b32_e32 v138, v70
	v_mov_b32_e32 v139, v71
	v_mov_b32_e32 v140, v72
	v_mov_b32_e32 v141, v73
	v_mov_b32_e32 v142, v74
	v_mov_b32_e32 v143, v75
	v_mov_b32_e32 v144, v76
	v_mov_b32_e32 v145, v77
	v_mov_b32_e32 v146, v78
	v_mov_b32_e32 v147, v79
	v_mov_b32_e32 v148, v81
	v_mov_b32_e32 v149, v82
	v_mov_b32_e32 v150, v83
	v_mov_b32_e32 v151, v84
	v_mov_b32_e32 v152, v85
	v_mov_b32_e32 v153, v86
	v_mov_b32_e32 v154, v87
	v_mov_b32_e32 v155, v88
	v_mov_b32_e32 v156, v89
	v_mov_b32_e32 v157, v90
	v_mov_b32_e32 v158, v91
	v_writelane_b32 v253, s1, 0
	v_writelane_b32 v253, s22, 1
	v_writelane_b32 v253, s30, 2
	v_writelane_b32 v253, s31, 3
	v_writelane_b32 v253, s34, 4
	v_writelane_b32 v253, s35, 5
	v_writelane_b32 v253, s36, 6
	v_writelane_b32 v253, s37, 7
	v_writelane_b32 v253, s38, 8
	v_writelane_b32 v253, s39, 9
	v_writelane_b32 v253, s41, 10
	v_writelane_b32 v253, s44, 11
	v_writelane_b32 v253, s45, 12
	v_writelane_b32 v253, s46, 13
	v_writelane_b32 v253, s47, 14
	v_writelane_b32 v253, s48, 15
	v_writelane_b32 v253, s49, 16
	v_writelane_b32 v253, s50, 17
	v_writelane_b32 v253, s51, 18
	v_writelane_b32 v253, s52, 19
	v_writelane_b32 v253, s54, 20
	v_writelane_b32 v253, s63, 21
	v_writelane_b32 v253, s64, 22
	v_writelane_b32 v253, s65, 23
	v_writelane_b32 v253, s70, 24
	v_writelane_b32 v253, s71, 25
	v_writelane_b32 v253, s72, 26
	v_writelane_b32 v253, s74, 27
	v_writelane_b32 v253, s75, 28
	v_writelane_b32 v253, s77, 29
	v_writelane_b32 v253, s82, 30
	v_writelane_b32 v253, s83, 31
	v_writelane_b32 v253, s84, 32
	v_writelane_b32 v253, s85, 33
	v_and_b32_e32 v80, 63, v201
	v_readlane_b32 s24, v252, 15
	v_readlane_b32 s25, v252, 16
	s_nop 3
	s_load_dwordx2 s[4:5], s[24:25], 0xa8
	v_readlane_b32 s1, v252, 2
	v_readlane_b32 s14, v252, 1
	s_nop 3
	s_add_i32 s1, s1, s14
	s_add_i32 s1, s1, 0x200
	v_lshlrev_b32_e32 v0, 2, v80
	s_waitcnt lgkmcnt(0)
	s_add_u32 s26, s4, 0x5400000
	s_addc_u32 s27, s5, 0
	s_add_u32 s34, s4, 0x3300000
	s_addc_u32 s35, s5, 0
	s_add_u32 s36, s4, 0x1900000
	s_addc_u32 s37, s5, 0
	s_add_u32 s38, s4, 0xb00000
	s_addc_u32 s39, s5, 0
	s_lshl_b32 s3, s1, 6
	v_and_b32_e32 v81, 0x80, v0
	v_or_b32_e32 v82, s3, v80
	s_lshl_b32 s4, s1, 5
	s_lshl_b32 s5, s1, 2
	v_mov_b32_e32 v13, 0
	s_movk_i32 s30, 0x7fff
	s_mov_b32 s31, 0xffff0000
	v_mov_b32_e32 v83, 0x2000
	v_mov_b32_e32 v84, 1
	s_mov_b32 s33, 0x1439000
	s_mov_b32 s44, 0x143c000
	s_mov_b32 s45, 0x143e000
	s_mov_b32 s46, 0x1441000
	s_mov_b32 s47, 0x1443000
	s_mov_b32 s48, 0x1446000
	s_mov_b32 s49, 0x1448000
	s_mov_b32 s50, 0x144b000
	s_mov_b32 s51, 0x144d000
	s_mov_b32 s52, 0x1450000
	s_mov_b32 s53, 0x1452000
	s_mov_b32 s54, 0x1455000
	s_mov_b32 s55, 0x1457000
	s_mov_b32 s56, 0x145a000
	s_mov_b32 s57, 0x145c000
	s_mov_b32 s58, 0x145f000
	s_mov_b32 s59, 0x1461000
	s_mov_b32 s60, 0x1464000
	s_mov_b32 s61, 0x1466000
	s_mov_b32 s62, 0x1469000
	s_mov_b32 s63, 0x146b000
	s_mov_b32 s64, 0x146e000
	s_mov_b32 s65, 0x1470000
	s_mov_b32 s66, 0x1473000
	s_mov_b32 s67, 0x1475000
	s_mov_b32 s68, 0x1478000
	s_mov_b32 s69, 0x147a000
	s_mov_b32 s70, 0x147d000
	s_mov_b32 s71, 0x147f000
	s_mov_b32 s72, 0x1482000
	s_mov_b32 s73, 0x1484000
	s_mov_b32 s74, 0x1487000
	s_mov_b32 s75, 0x1489000
	s_mov_b32 s76, 0x148c000
	s_mov_b32 s77, 0x148e000
	s_mov_b32 s78, 0x1491000
	s_mov_b32 s79, 0x1493000
	s_mov_b32 s80, 0x1496000
	s_mov_b32 s81, 0x1498000
	s_mov_b32 s82, 0x149b000
	s_mov_b32 s83, 0x149d000
	s_mov_b32 s41, 0
	s_branch .Lcsc1_681

; __device__ __forceinline__ unsigned pk2(float lo, float hi) { return f2bf(lo) | (f2bf(hi) << 16); }
; __device__ __forceinline__ void transpose_item(const float* __restrict__ W, int K, int N, bf16* __restrict__ WT, const float* __restrict__ ksc, int mode, int row_off, int item, int lane) {
;     const int nblk = N / 64, kb = item / nblk, nb = item % nblk, k0 = 64 * kb, n = 64 * nb + lane;
;     const float* src = W + (size_t)k0 * N + n;
;     float v[64];
; #pragma unroll
;     for (int i = 0; i < 64; ++i) v[i] = __builtin_nontemporal_load(src + (size_t)i * N);
;     if (ksc) {
; #pragma unroll
;         for (int i = 0; i < 64; ++i) v[i] *= ksc[k0 + i];
;     }
;     bf16* dst = WT + (size_t)(row_off + map_row(n, mode)) * K + k0;
; #pragma unroll
;     for (int j = 0; j < 8; ++j) { v4u o; o.x = pk2(v[8 * j], v[8 * j + 1]); o.y = pk2(v[8 * j + 2], v[8 * j + 3]); o.z = pk2(v[8 * j + 4], v[8 * j + 5]); o.w = pk2(v[8 * j + 6], v[8 * j + 7]);
;         *(v4u*)(dst + 8 * j) = o; }
; __device__ __forceinline__ void convert_layer(ArgsP a, int L, int first, int stride, int lane) {
;     ...
;     for (int r = first; r < I_L; r += stride) {
;         if (r < I_IN) transpose_item(a->in[3] + (size_t)L * D * INW, D, INW, WIN + (size_t)L * INW * D, a->in[2] + L * D, 1, 0, r, lane);
;         else if (r < I_IN + I_OUT) transpose_item(a->in[4] + (size_t)L * D * D, D, D, WOUT + (size_t)L * D * D, nullptr, 0, 0, r - I_IN, lane);
;         else if (r < I_IN + I_OUT + I_GU) transpose_item(a->in[18] + (size_t)L * D * GU, D, GU, WGU + (size_t)L * GU * D, a->in[17] + L * D, 2, 0, r - I_IN - I_OUT, lane);
;         else transpose_item(a->in[19] + (size_t)L * FFN * D, FFN, D, WDN + (size_t)L * D * FFN, nullptr, 0, 0, r - I_IN - I_OUT - I_GU, lane);
;     }
.Lcsc1_680:
	s_add_i32 s14, s1, 0x400
	s_add_i32 s4, s4, 0x8000
	s_addk_i32 s5, 0x1000
	s_add_i32 s3, s3, 0x10000
	v_add_u32_e32 v82, 0x10000, v82
	s_cmpk_lt_i32 s1, 0x7c0
	s_mov_b32 s1, s14
	global_store_dwordx4 v[78:79], v[0:3], off offset:112
	s_cbranch_scc0 .Lcsc1_700

; #define PG8_LAS __attribute__((address_space(3)))
; #define PG8_WAIT_V(n) asm volatile("s_waitcnt vmcnt(" #n ")" ::: "memory")
; template <class Epi, class Sched, bool ALIGN_EPI = false, bool SP2 = false>
; __device__ __forceinline__ void gemm_phase(PG8_LAS unsigned char* lds, const Gemm g, const Sched& S, const Epi& E, int tid_in) {
;     int tid_ = tid_in; asm volatile("" : "+v"(tid_));
;     const int tid = tid_, wid = __builtin_amdgcn_readfirstlane(tid >> 6), lane = tid & 63, wr = wid >> 2, wc = wid & 3, fr = lane & 15, fq = lane >> 4;
;     const int K = g.K, nt = K / BK;
;     unsigned voffA[2], voffB[2];
; #pragma unroll
;     for (int i = 0; i < 2; ++i) { int R, C; stage_rc(tid * 16 + i * 8192, R, C); const int Rb = Epi::PERM ? ((R & ~31) + perm32(R & 31)) : R;
;         voffA[i] = (unsigned)(R * K + C) * 2u; voffB[i] = (unsigned)(Rb * K + C) * 2u; }
;     const size_t kstep = (size_t)(BK * 2);
;     const size_t hstep = (size_t)HALF * K * 2;
;     const size_t tstep = 2 * hstep;
;     const unsigned ldsw = (unsigned)wid * 1024u;
;     const int aoff = lds_byte(wr * 64 + fr, fq * 8), boff = lds_byte(wc * 32 + fr, fq * 8);
;     ...
;     Unit cur, nxt; int ui = 0;
;     if (!S.next(0, cur)) return;
;     f32x4 acc[2][2][4][2];
; #pragma unroll
;     for (int a = 0; a < 2; ++a)
; #pragma unroll
;         for (int b = 0; b < 2; ++b)
; #pragma unroll
;             for (int m = 0; m < 4; ++m)
; #pragma unroll
;                 for (int n = 0; n < 2; ++n) acc[a][b][m][n] = (f32x4){0.f, 0.f, 0.f, 0.f};
;     bf16x8 At[4][2], B0[2][2], B1[2][2];
;     const char* cA = (const char*)g.A + (size_t)cur.pm * tstep; const char* cB = (const char*)g.Bt + (size_t)cur.pn * tstep;
;     S.a_ready(cur);
;     if constexpr (SP2) {
;         PG8_STAGE(PG8_SB(0, 0), cB, voffB); PG8_STAGE(PG8_SB(0, 1), cB + hstep, voffB); PG8_STAGE(PG8_SA(0, 0), cA, voffA); PG8_STAGE(PG8_SA(0, 1), cA + hstep, voffA);
;         if (wr == 1) PG8_BAR;
;         PG8_WAIT_V(2); PG8_BAR;
;         PG8_STAGE(PG8_SB(1, 0), cB + kstep, voffB); PG8_STAGE(PG8_SA(1, 0), cA + kstep, voffA); PG8_STAGE(PG8_SB(1, 1), cB + hstep + kstep, voffB);
;         PG8_WAIT_V(6); PG8_BAR;
;     } else {
;         PG8_STAGE(PG8_SB(0, 0), cB, voffB); PG8_STAGE(PG8_SA(0, 0), cA, voffA); PG8_STAGE(PG8_SB(0, 1), cB + hstep, voffB); PG8_STAGE(PG8_SA(0, 1), cA + hstep, voffA);
;         if (wr == 1) PG8_BAR;
.Lcsc1_700:
	s_waitcnt vmcnt(0)
	v_mov_b32_e32 v0, v128
	v_mov_b32_e32 v1, v129
	v_mov_b32_e32 v2, v130
	v_mov_b32_e32 v3, v131
	v_mov_b32_e32 v64, v132
	v_mov_b32_e32 v65, v133
	v_mov_b32_e32 v66, v134
	v_mov_b32_e32 v67, v135
	v_mov_b32_e32 v68, v136
	v_mov_b32_e32 v69, v137
	v_mov_b32_e32 v70, v138
	v_mov_b32_e32 v71, v139
	v_mov_b32_e32 v72, v140
	v_mov_b32_e32 v73, v141
	v_mov_b32_e32 v74, v142
	v_mov_b32_e32 v75, v143
	v_mov_b32_e32 v76, v144
	v_mov_b32_e32 v77, v145
	v_mov_b32_e32 v78, v146
	v_mov_b32_e32 v79, v147
	v_mov_b32_e32 v81, v148
	v_mov_b32_e32 v82, v149
	v_mov_b32_e32 v83, v150
	v_mov_b32_e32 v84, v151
	v_mov_b32_e32 v85, v152
	v_mov_b32_e32 v86, v153
	v_mov_b32_e32 v87, v154
	v_mov_b32_e32 v88, v155
	v_mov_b32_e32 v89, v156
	v_mov_b32_e32 v90, v157
	v_mov_b32_e32 v91, v158
	v_readlane_b32 s1, v253, 0
	v_readlane_b32 s22, v253, 1
	v_readlane_b32 s30, v253, 2
	v_readlane_b32 s31, v253, 3
	v_readlane_b32 s34, v253, 4
	v_readlane_b32 s35, v253, 5
	v_readlane_b32 s36, v253, 6
	v_readlane_b32 s37, v253, 7
	v_readlane_b32 s38, v253, 8
	v_readlane_b32 s39, v253, 9
	v_readlane_b32 s41, v253, 10
	v_readlane_b32 s44, v253, 11
	v_readlane_b32 s45, v253, 12
	v_readlane_b32 s46, v253, 13
	v_readlane_b32 s47, v253, 14
	v_readlane_b32 s48, v253, 15
	v_readlane_b32 s49, v253, 16
	v_readlane_b32 s50, v253, 17
	v_readlane_b32 s51, v253, 18
	v_readlane_b32 s52, v253, 19
	v_readlane_b32 s54, v253, 20
	v_readlane_b32 s63, v253, 21
	v_readlane_b32 s64, v253, 22
	v_readlane_b32 s65, v253, 23
	v_readlane_b32 s70, v253, 24
	v_readlane_b32 s71, v253, 25
	v_readlane_b32 s72, v253, 26
	v_readlane_b32 s74, v253, 27
	v_readlane_b32 s75, v253, 28
	v_readlane_b32 s77, v253, 29
	v_readlane_b32 s82, v253, 30
	v_readlane_b32 s83, v253, 31
	v_readlane_b32 s84, v253, 32
	v_readlane_b32 s85, v253, 33
	s_nop 4
.Lcsc1_skip:
	v_readlane_b32 s0, v252, 5
	s_andn2_b64 vcc, exec, s[42:43]
	s_nop 0
	v_and_or_b32 v8, v0, 63, s0
	v_cndmask_b32_e64 v0, 0, 1, s[42:43]
	v_cmp_ne_u32_e64 s[4:5], 1, v0
	s_nop 0
	v_readfirstlane_b32 s25, v8
	v_writelane_b32 v252, s4, 33
	s_nop 1
	v_writelane_b32 v252, s5, 34
	s_cbranch_vccnz .LBB0_1003
	v_lshlrev_b32_e32 v0, 4, v8
	v_add_u32_e32 v1, 0x2000, v0
	v_ashrrev_i32_e32 v2, 31, v1
	v_lshrrev_b32_e32 v2, 22, v2
	v_add_u32_e32 v2, v1, v2
	v_ashrrev_i32_e32 v9, 10, v2
	v_mul_i32_i24_e32 v2, 0x400, v9
	v_sub_u32_e32 v1, v1, v2
	v_lshrrev_b32_e32 v2, 4, v1
	v_bitop3_b32 v1, v2, v1, 32 bitop3:0x6c
	v_ashrrev_i32_e32 v2, 31, v1
	v_lshrrev_b32_e32 v2, 26, v2
	v_add_u32_e32 v2, v1, v2
	v_lshlrev_b32_e32 v3, 3, v9
	v_ashrrev_i32_e32 v10, 6, v2
	v_and_b32_e32 v3, -16, v3
	v_add_u32_e32 v3, v10, v3
	v_and_b32_e32 v4, 3, v10
	s_mov_b32 s4, 0x1fffe0
	v_lshrrev_b32_e32 v5, 2, v3
	v_lshlrev_b32_e32 v6, 1, v3
	v_and_b32_e32 v2, 0xc0, v2
	v_and_or_b32 v4, v3, s4, v4
	v_and_b32_e32 v5, 4, v5
	v_and_b32_e32 v6, 24, v6
	v_sub_u32_e32 v1, v1, v2
	v_mov_b32_e32 v2, 1
	v_or3_b32 v4, v4, v5, v6
	v_lshlrev_b32_e32 v5, 5, v9
	v_ashrrev_i16_sdwa v1, v2, sext(v1) dst_sel:DWORD dst_unused:UNUSED_PAD src0_sel:DWORD src1_sel:BYTE_0
	v_and_b32_e32 v5, 32, v5
	v_bfe_i32 v11, v1, 0, 16
	v_add_lshl_u32 v1, v5, v11, 1
	v_lshl_add_u32 v128, v4, 11, v1
	v_lshl_add_u32 v130, v3, 11, v1
	v_bfe_i32 v1, v8, 27, 1
	v_lshrrev_b32_e32 v1, 22, v1
	v_add_u32_e32 v1, v0, v1
	s_load_dwordx2 s[16:17], s[16:17], 0xa8
	v_and_b32_e32 v1, 0xfffffc00, v1
	v_sub_u32_e32 v0, v0, v1
	v_lshrrev_b32_e32 v1, 4, v0
	v_ashrrev_i32_e32 v3, 31, v8
	v_bitop3_b32 v0, v1, v0, 32 bitop3:0x6c
	v_lshrrev_b32_e32 v3, 26, v3
	v_ashrrev_i32_e32 v1, 31, v0
	v_add_u32_e32 v3, v8, v3
	s_waitcnt lgkmcnt(0)
	s_add_u32 s0, s16, 0x6900000
	v_lshrrev_b32_e32 v1, 26, v1
	v_ashrrev_i32_e32 v13, 6, v3
	s_addc_u32 s3, s17, 0
	v_add_u32_e32 v1, v0, v1
	v_lshlrev_b32_e32 v3, 3, v13
	s_add_u32 s12, s16, 0x2800000
	v_ashrrev_i32_e32 v12, 6, v1
	v_and_b32_e32 v3, -16, v3
	s_addc_u32 s13, s17, 0
	v_add_u32_e32 v3, v12, v3
	v_and_b32_e32 v4, 3, v12
	s_ashr_i32 s40, s2, 31
	v_and_or_b32 v4, v3, s4, v4
	s_lshr_b32 s4, s40, 29
	s_add_i32 s4, s2, s4
	s_ashr_i32 s22, s25, 6
	s_ashr_i32 s5, s4, 3
	s_and_b32 s4, s4, -8
	s_ashr_i32 s26, s25, 8
	s_lshl_b32 s33, s22, 10
	s_sub_i32 s4, s2, s4
	s_cmp_lt_i32 s4, 0
	s_movk_i32 s56, 0xb1
	s_cselect_b32 s14, s56, 0xb0
	s_mul_i32 s4, s14, s4
	s_add_i32 s4, s4, s5
	s_mul_hi_i32 s5, s4, 0x2e8ba2e9
	s_lshr_b32 s14, s5, 31
	s_ashr_i32 s5, s5, 5
	s_add_i32 s5, s5, s14
	s_lshl_b32 s14, s5, 3
	s_mulk_i32 s5, 0xb0
	s_sub_i32 s4, s4, s5
	s_sext_i32_i16 s5, s4
	s_bfe_u32 s5, s5, 0x3001c
	s_add_i32 s5, s4, s5
	s_sext_i32_i16 s15, s5
	s_and_b32 s5, s5, 0xfff8
	s_sub_i32 s4, s4, s5
	s_sext_i32_i16 s4, s4
	v_lshrrev_b32_e32 v5, 2, v3
	v_lshlrev_b32_e32 v6, 1, v3
	v_and_b32_e32 v1, 0xc0, v1
	s_lshr_b32 s24, s15, 3
	s_add_i32 s48, s14, s4
	v_and_b32_e32 v5, 4, v5
	v_and_b32_e32 v6, 24, v6
	v_sub_u32_e32 v0, v0, v1
	s_ashr_i32 s49, s48, 31
	s_bfe_i64 s[18:19], s[24:25], 0x100000
	v_or3_b32 v4, v4, v5, v6
	v_lshlrev_b32_e32 v5, 5, v13
	v_ashrrev_i16_sdwa v0, v2, sext(v0) dst_sel:DWORD dst_unused:UNUSED_PAD src0_sel:DWORD src1_sel:BYTE_0
	s_lshl_b64 s[14:15], s[48:49], 19
	s_lshl_b64 s[18:19], s[18:19], 19
	v_and_b32_e32 v5, 32, v5
	v_bfe_i32 v14, v0, 0, 16
	s_add_u32 s50, s12, s18
	v_add_lshl_u32 v0, v5, v14, 1
	s_addc_u32 s51, s13, s19
	s_add_i32 s57, s33, 0
	v_lshl_add_u32 v132, v4, 11, v0
	s_add_i32 m0, s57, 0x10000
	v_lshl_add_u32 v134, v3, 11, v0
	global_load_lds_dwordx4 v132, s[50:51]
	s_add_i32 m0, s57, 0x12000
	s_add_u32 s18, s50, 0x40000
	global_load_lds_dwordx4 v128, s[50:51]
	s_addc_u32 s19, s51, 0
	s_add_i32 m0, s57, 0x14000
	v_mov_b32_e32 v133, 0
	global_load_lds_dwordx4 v132, s[18:19]
	s_add_i32 m0, s57, 0x16000
	s_add_u32 s52, s0, s14
	s_addc_u32 s53, s3, s15
	s_add_i32 s58, s57, 0x2000
	global_load_lds_dwordx4 v128, s[18:19]
	s_mov_b32 m0, s57
	s_add_u32 s14, s52, 0x40000
	global_load_lds_dwordx4 v134, s[52:53]
	s_mov_b32 m0, s58
	s_addc_u32 s15, s53, 0
	s_add_i32 s59, s57, 0x4000
	global_load_lds_dwordx4 v130, s[52:53]
	s_mov_b32 m0, s59
	s_add_i32 s60, s57, 0x6000
	global_load_lds_dwordx4 v134, s[14:15]
	s_mov_b32 m0, s60
	v_mov_b32_e32 v129, v133
	global_load_lds_dwordx4 v130, s[14:15]
	v_mov_b32_e32 v135, v133
	v_mov_b32_e32 v131, v133
	s_cmp_eq_u32 s26, 1
	s_mov_b32 s61, 0
	v_lshl_add_u64 v[6:7], s[50:51], 0, v[132:133]
	v_lshl_add_u64 v[4:5], s[50:51], 0, v[128:129]
	v_lshl_add_u64 v[0:1], s[52:53], 0, v[134:135]
	s_cselect_b64 s[18:19], -1, 0
	s_cmp_lg_u32 s26, 1
	v_lshl_add_u64 v[2:3], s[52:53], 0, v[130:131]
	s_cbranch_scc1 .LBB0_990
	s_barrier

; __device__ __forceinline__ ArgsP args_ptr() { ArgsP p = (ArgsP)__builtin_amdgcn_kernarg_segment_ptr(); asm volatile("" : "+s"(p)); return p; }
; __device__ __forceinline__ void convert_layer(ArgsP a, int L, int first, int stride, int lane) {
;     ...
;     for (int r = first; r < I_L; r += stride) {
;         if (r < I_IN) transpose_item(a->in[3] + (size_t)L * D * INW, D, INW, WIN + (size_t)L * INW * D, a->in[2] + L * D, 1, 0, r, lane);
;         else if (r < I_IN + I_OUT) transpose_item(a->in[4] + (size_t)L * D * D, D, D, WOUT + (size_t)L * D * D, nullptr, 0, 0, r - I_IN, lane);
;         else if (r < I_IN + I_OUT + I_GU) transpose_item(a->in[18] + (size_t)L * D * GU, D, GU, WGU + (size_t)L * GU * D, a->in[17] + L * D, 2, 0, r - I_IN - I_OUT, lane);
;         else transpose_item(a->in[19] + (size_t)L * FFN * D, FFN, D, WDN + (size_t)L * D * FFN, nullptr, 0, 0, r - I_IN - I_OUT - I_GU, lane);
;     }
; __device__ __forceinline__ void phase_A(unsigned char* lds, int wave_s, int L) {
;     ...
;     if (L + 1 < DEPTH && bx >= 128 && bx < 224) { convert_layer(args_ptr(), L + 1, (bx - 128) * NWAVES + wave, 96 * NWAVES, lane); asm volatile("s_waitcnt vmcnt(0)" ::: "memory"); }
.LBB0_1156:
	s_add_i32 s0, s3, 0x300
	s_addk_i32 s13, 0x6000
	s_addk_i32 s40, 0xc00
	s_add_i32 s12, s12, 0xc000
	v_add_u32_e32 v82, 0xc000, v82
	s_cmpk_lt_i32 s3, 0x300
	s_mov_b32 s3, s0
	global_store_dwordx4 v[78:79], v[0:3], off offset:112
	s_cbranch_scc0 .LBB0_1176

; __device__ __forceinline__ ArgsP args_ptr() { ArgsP p = (ArgsP)__builtin_amdgcn_kernarg_segment_ptr(); asm volatile("" : "+s"(p)); return p; }
; #define TIDS() int lane_ = (int)__builtin_amdgcn_mbcnt_hi(~0u, __builtin_amdgcn_mbcnt_lo(~0u, 0u)); asm volatile("" : "+v"(lane_)); const int lane = lane_ & 63, wave = wave_s & 7, tid = wave * 64 + lane; const int G = gridDim.x, bx = blockIdx.x; (void)lane; (void)wave; (void)tid; (void)G; (void)bx
; __device__ __forceinline__ void convert_layer(ArgsP a, int L, int first, int stride, int lane) {
;     unsigned char* ws = a->ws;
;     bf16* WIN = (bf16*)(ws + WS_WIN); bf16* WOUT = (bf16*)(ws + WS_WOUT); bf16* WGU = (bf16*)(ws + WS_WGU); bf16* WDN = (bf16*)(ws + WS_WDN);
;     for (int r = first; r < I_L; r += stride) {
;         if (r < I_IN) transpose_item(a->in[3] + (size_t)L * D * INW, D, INW, WIN + (size_t)L * INW * D, a->in[2] + L * D, 1, 0, r, lane);
;         else if (r < I_IN + I_OUT) transpose_item(a->in[4] + (size_t)L * D * D, D, D, WOUT + (size_t)L * D * D, nullptr, 0, 0, r - I_IN, lane);
;         else if (r < I_IN + I_OUT + I_GU) transpose_item(a->in[18] + (size_t)L * D * GU, D, GU, WGU + (size_t)L * GU * D, a->in[17] + L * D, 2, 0, r - I_IN - I_OUT, lane);
;         else transpose_item(a->in[19] + (size_t)L * FFN * D, FFN, D, WDN + (size_t)L * D * FFN, nullptr, 0, 0, r - I_IN - I_OUT - I_GU, lane);
;     }
; }
; __device__ __forceinline__ void phase_D(unsigned char* lds, int wave_s, int L) {
;     ArgsP a = args_ptr(); TIDS(); unsigned char* ws = a->ws;
;     pg8::Gemm g{(bf16*)(ws + WS_XB), (bf16*)(ws + WS_WGU) + (size_t)L * GU * D, M, GU, D}; pg8::StaticOrder S; S.init(M, GU, G, bx);
;     pg8::EpiSwi E{(bf16*)(ws + WS_ACT), (const float*)(ws + WS_SS)};
;     pg8::gemm_phase<pg8::EpiSwi, pg8::StaticOrder, true, true>((pg8::PG8_LAS_T*)lds, g, S, E, tid);
.LBB0_1579:
	s_or_b64 exec, exec, s[8:9]
	v_readlane_b32 s8, v252, 15
	v_readlane_b32 s9, v252, 16
	s_waitcnt lgkmcnt(0)
	v_mov_b32_e32 v0, v201
	v_readlane_b32 s0, v252, 5
	v_readlane_b32 s4, v252, 33
	s_barrier
	s_cmp_lt_u32 s2, 0x80
	s_cbranch_scc1 .Lcsc2_skip
	v_mov_b32_e32 v128, v0
	v_mov_b32_e32 v129, v2
	v_mov_b32_e32 v130, v3
	v_mov_b32_e32 v131, v64
	v_mov_b32_e32 v132, v65
	v_mov_b32_e32 v133, v66
	v_mov_b32_e32 v134, v67
	v_mov_b32_e32 v135, v68
	v_mov_b32_e32 v136, v69
	v_mov_b32_e32 v137, v70
	v_mov_b32_e32 v138, v71
	v_mov_b32_e32 v139, v72
	v_mov_b32_e32 v140, v73
	v_mov_b32_e32 v141, v74
	v_mov_b32_e32 v142, v75
	v_mov_b32_e32 v143, v76
	v_mov_b32_e32 v144, v77
	v_mov_b32_e32 v145, v78
	v_mov_b32_e32 v146, v79
	v_mov_b32_e32 v147, v80
	v_mov_b32_e32 v148, v81
	v_mov_b32_e32 v149, v82
	v_mov_b32_e32 v150, v83
	v_mov_b32_e32 v151, v84
	v_mov_b32_e32 v152, v85
	v_mov_b32_e32 v153, v86
	v_mov_b32_e32 v154, v87
	v_mov_b32_e32 v155, v88
	v_mov_b32_e32 v156, v89
	v_mov_b32_e32 v157, v90
	v_mov_b32_e32 v158, v91
	v_writelane_b32 v253, s0, 0
	v_writelane_b32 v253, s4, 1
	v_writelane_b32 v253, s18, 2
	v_writelane_b32 v253, s42, 3
	v_writelane_b32 v253, s43, 4
	v_writelane_b32 v253, s44, 5
	v_writelane_b32 v253, s45, 6
	v_writelane_b32 v253, s46, 7
	v_writelane_b32 v253, s47, 8
	v_writelane_b32 v253, s50, 9
	v_and_b32_e32 v80, 63, v201
	v_readlane_b32 s14, v252, 15
	v_readlane_b32 s15, v252, 16
	s_load_dwordx2 s[12:13], s[14:15], 0xa8
	v_readlane_b32 s0, v252, 1
	v_readlane_b32 s3, v252, 2
	s_add_i32 s0, s3, s0
	s_add_i32 s3, s0, 0x200
	s_waitcnt lgkmcnt(0)
	s_add_u32 s20, s12, 0x5980000
	s_addc_u32 s21, s13, 0
	s_add_u32 s22, s12, 0x3e00000
	s_addc_u32 s23, s13, 0
	s_add_u32 s42, s12, 0x1b00000
	s_addc_u32 s43, s13, 0
	s_add_u32 s44, s12, 0x1000000
	v_lshlrev_b32_e32 v0, 2, v80
	s_addc_u32 s45, s13, 0
	s_lshl_b32 s12, s3, 6
	v_and_b32_e32 v81, 0x80, v0
	v_or_b32_e32 v82, s12, v80
	s_lshl_b32 s13, s3, 5
	s_lshl_b32 s40, s3, 2
	v_mov_b32_e32 v13, 0
	s_movk_i32 s48, 0x7fff
	s_mov_b32 s49, 0xffff0000
	v_mov_b32_e32 v83, 0x3000
	v_mov_b32_e32 v84, 1
	s_mov_b32 s50, 0x1e9b000
	s_mov_b32 s51, 0x1e9d000
	s_mov_b32 s47, 0
	s_branch .Lcsc2_1157

; __device__ __forceinline__ unsigned pk2(float lo, float hi) { return f2bf(lo) | (f2bf(hi) << 16); }
; __device__ __forceinline__ void transpose_item(const float* __restrict__ W, int K, int N, bf16* __restrict__ WT, const float* __restrict__ ksc, int mode, int row_off, int item, int lane) {
;     const int nblk = N / 64, kb = item / nblk, nb = item % nblk, k0 = 64 * kb, n = 64 * nb + lane;
;     const float* src = W + (size_t)k0 * N + n;
;     float v[64];
; #pragma unroll
;     for (int i = 0; i < 64; ++i) v[i] = __builtin_nontemporal_load(src + (size_t)i * N);
;     if (ksc) {
; #pragma unroll
;         for (int i = 0; i < 64; ++i) v[i] *= ksc[k0 + i];
;     }
;     bf16* dst = WT + (size_t)(row_off + map_row(n, mode)) * K + k0;
; #pragma unroll
;     for (int j = 0; j < 8; ++j) { v4u o; o.x = pk2(v[8 * j], v[8 * j + 1]); o.y = pk2(v[8 * j + 2], v[8 * j + 3]); o.z = pk2(v[8 * j + 4], v[8 * j + 5]); o.w = pk2(v[8 * j + 6], v[8 * j + 7]);
;         *(v4u*)(dst + 8 * j) = o; }
; __device__ __forceinline__ void convert_layer(ArgsP a, int L, int first, int stride, int lane) {
;     ...
;     for (int r = first; r < I_L; r += stride) {
;         if (r < I_IN) transpose_item(a->in[3] + (size_t)L * D * INW, D, INW, WIN + (size_t)L * INW * D, a->in[2] + L * D, 1, 0, r, lane);
;         else if (r < I_IN + I_OUT) transpose_item(a->in[4] + (size_t)L * D * D, D, D, WOUT + (size_t)L * D * D, nullptr, 0, 0, r - I_IN, lane);
;         else if (r < I_IN + I_OUT + I_GU) transpose_item(a->in[18] + (size_t)L * D * GU, D, GU, WGU + (size_t)L * GU * D, a->in[17] + L * D, 2, 0, r - I_IN - I_OUT, lane);
;         else transpose_item(a->in[19] + (size_t)L * FFN * D, FFN, D, WDN + (size_t)L * D * FFN, nullptr, 0, 0, r - I_IN - I_OUT - I_GU, lane);
;     }
.Lcsc2_1156:
	s_add_i32 s0, s3, 0x400
	s_add_i32 s13, s13, 0x8000
	s_addk_i32 s40, 0x1000
	s_add_i32 s12, s12, 0x10000
	v_add_u32_e32 v82, 0x10000, v82
	s_cmpk_lt_i32 s3, 0x7c0
	s_mov_b32 s3, s0
	global_store_dwordx4 v[78:79], v[0:3], off offset:112
	s_cbranch_scc0 .Lcsc2_1176

; #define PG8_LAS __attribute__((address_space(3)))
; #define PG8_WAIT_V(n) asm volatile("s_waitcnt vmcnt(" #n ")" ::: "memory")
; template <class Epi, class Sched, bool ALIGN_EPI = false, bool SP2 = false>
; __device__ __forceinline__ void gemm_phase(PG8_LAS unsigned char* lds, const Gemm g, const Sched& S, const Epi& E, int tid_in) {
;     int tid_ = tid_in; asm volatile("" : "+v"(tid_));
;     const int tid = tid_, wid = __builtin_amdgcn_readfirstlane(tid >> 6), lane = tid & 63, wr = wid >> 2, wc = wid & 3, fr = lane & 15, fq = lane >> 4;
;     const int K = g.K, nt = K / BK;
;     unsigned voffA[2], voffB[2];
; #pragma unroll
;     for (int i = 0; i < 2; ++i) { int R, C; stage_rc(tid * 16 + i * 8192, R, C); const int Rb = Epi::PERM ? ((R & ~31) + perm32(R & 31)) : R;
;         voffA[i] = (unsigned)(R * K + C) * 2u; voffB[i] = (unsigned)(Rb * K + C) * 2u; }
;     const size_t kstep = (size_t)(BK * 2);
;     const size_t hstep = (size_t)HALF * K * 2;
;     const size_t tstep = 2 * hstep;
;     const unsigned ldsw = (unsigned)wid * 1024u;
;     const int aoff = lds_byte(wr * 64 + fr, fq * 8), boff = lds_byte(wc * 32 + fr, fq * 8);
;     ...
;     Unit cur, nxt; int ui = 0;
;     if (!S.next(0, cur)) return;
;     f32x4 acc[2][2][4][2];
; #pragma unroll
;     for (int a = 0; a < 2; ++a)
; #pragma unroll
;         for (int b = 0; b < 2; ++b)
; #pragma unroll
;             for (int m = 0; m < 4; ++m)
; #pragma unroll
;                 for (int n = 0; n < 2; ++n) acc[a][b][m][n] = (f32x4){0.f, 0.f, 0.f, 0.f};
;     bf16x8 At[4][2], B0[2][2], B1[2][2];
;     const char* cA = (const char*)g.A + (size_t)cur.pm * tstep; const char* cB = (const char*)g.Bt + (size_t)cur.pn * tstep;
;     S.a_ready(cur);
;     if constexpr (SP2) {
;         PG8_STAGE(PG8_SB(0, 0), cB, voffB); PG8_STAGE(PG8_SB(0, 1), cB + hstep, voffB); PG8_STAGE(PG8_SA(0, 0), cA, voffA); PG8_STAGE(PG8_SA(0, 1), cA + hstep, voffA);
;         if (wr == 1) PG8_BAR;
;         PG8_WAIT_V(2); PG8_BAR;
;         PG8_STAGE(PG8_SB(1, 0), cB + kstep, voffB); PG8_STAGE(PG8_SA(1, 0), cA + kstep, voffA); PG8_STAGE(PG8_SB(1, 1), cB + hstep + kstep, voffB);
;         PG8_WAIT_V(6); PG8_BAR;
;     } else {
;         PG8_STAGE(PG8_SB(0, 0), cB, voffB); PG8_STAGE(PG8_SA(0, 0), cA, voffA); PG8_STAGE(PG8_SB(0, 1), cB + hstep, voffB); PG8_STAGE(PG8_SA(0, 1), cA + hstep, voffA);
;         if (wr == 1) PG8_BAR;
.Lcsc2_1176:
	s_waitcnt vmcnt(0)
	v_mov_b32_e32 v0, v128
	v_mov_b32_e32 v2, v129
	v_mov_b32_e32 v3, v130
	v_mov_b32_e32 v64, v131
	v_mov_b32_e32 v65, v132
	v_mov_b32_e32 v66, v133
	v_mov_b32_e32 v67, v134
	v_mov_b32_e32 v68, v135
	v_mov_b32_e32 v69, v136
	v_mov_b32_e32 v70, v137
	v_mov_b32_e32 v71, v138
	v_mov_b32_e32 v72, v139
	v_mov_b32_e32 v73, v140
	v_mov_b32_e32 v74, v141
	v_mov_b32_e32 v75, v142
	v_mov_b32_e32 v76, v143
	v_mov_b32_e32 v77, v144
	v_mov_b32_e32 v78, v145
	v_mov_b32_e32 v79, v146
	v_mov_b32_e32 v80, v147
	v_mov_b32_e32 v81, v148
	v_mov_b32_e32 v82, v149
	v_mov_b32_e32 v83, v150
	v_mov_b32_e32 v84, v151
	v_mov_b32_e32 v85, v152
	v_mov_b32_e32 v86, v153
	v_mov_b32_e32 v87, v154
	v_mov_b32_e32 v88, v155
	v_mov_b32_e32 v89, v156
	v_mov_b32_e32 v90, v157
	v_mov_b32_e32 v91, v158
	v_readlane_b32 s0, v253, 0
	v_readlane_b32 s4, v253, 1
	v_readlane_b32 s18, v253, 2
	v_readlane_b32 s42, v253, 3
	v_readlane_b32 s43, v253, 4
	v_readlane_b32 s44, v253, 5
	v_readlane_b32 s45, v253, 6
	v_readlane_b32 s46, v253, 7
	v_readlane_b32 s47, v253, 8
	v_readlane_b32 s50, v253, 9
	s_nop 4
.Lcsc2_skip:
	v_readlane_b32 s5, v252, 34
	v_and_or_b32 v8, v0, 63, s0
	s_and_b64 vcc, exec, s[4:5]
	v_readfirstlane_b32 s21, v8
	s_cbranch_vccnz .LBB0_1595
	v_lshlrev_b32_e32 v0, 4, v8
	v_add_u32_e32 v1, 0x2000, v0
	v_ashrrev_i32_e32 v2, 31, v1
	v_lshrrev_b32_e32 v2, 22, v2
	v_add_u32_e32 v2, v1, v2
	v_ashrrev_i32_e32 v9, 10, v2
	v_mul_i32_i24_e32 v2, 0x400, v9
	v_sub_u32_e32 v1, v1, v2
	v_lshrrev_b32_e32 v2, 4, v1
	v_bitop3_b32 v1, v2, v1, 32 bitop3:0x6c
	v_ashrrev_i32_e32 v2, 31, v1
	v_lshrrev_b32_e32 v2, 26, v2
	v_add_u32_e32 v2, v1, v2
	v_lshlrev_b32_e32 v3, 3, v9
	v_ashrrev_i32_e32 v10, 6, v2
	v_and_b32_e32 v3, -16, v3
	v_add_u32_e32 v3, v10, v3
	v_and_b32_e32 v4, 3, v10
	s_mov_b32 s4, 0x1fffe0
	v_lshrrev_b32_e32 v5, 2, v3
	v_lshlrev_b32_e32 v6, 1, v3
	v_and_b32_e32 v2, 0xc0, v2
	v_and_or_b32 v4, v3, s4, v4
	v_and_b32_e32 v5, 4, v5
	v_and_b32_e32 v6, 24, v6
	v_sub_u32_e32 v1, v1, v2
	v_mov_b32_e32 v2, 1
	v_or3_b32 v4, v4, v5, v6
	v_lshlrev_b32_e32 v5, 5, v9
	v_ashrrev_i16_sdwa v1, v2, sext(v1) dst_sel:DWORD dst_unused:UNUSED_PAD src0_sel:DWORD src1_sel:BYTE_0
	v_and_b32_e32 v5, 32, v5
	v_bfe_i32 v11, v1, 0, 16
	v_add_lshl_u32 v1, v5, v11, 1
	v_lshl_add_u32 v128, v4, 11, v1
	v_lshl_add_u32 v130, v3, 11, v1
	v_bfe_i32 v1, v8, 27, 1
	v_lshrrev_b32_e32 v1, 22, v1
	v_add_u32_e32 v1, v0, v1
	s_load_dwordx2 s[8:9], s[8:9], 0xa8
	v_and_b32_e32 v1, 0xfffffc00, v1
	v_sub_u32_e32 v0, v0, v1
	v_lshrrev_b32_e32 v1, 4, v0
	v_ashrrev_i32_e32 v3, 31, v8
	v_bitop3_b32 v0, v1, v0, 32 bitop3:0x6c
	v_lshrrev_b32_e32 v3, 26, v3
	v_ashrrev_i32_e32 v1, 31, v0
	v_add_u32_e32 v3, v8, v3
	s_waitcnt lgkmcnt(0)
	s_add_u32 s0, s8, 0x6900000
	v_lshrrev_b32_e32 v1, 26, v1
	v_ashrrev_i32_e32 v13, 6, v3
	s_addc_u32 s3, s9, 0
	v_add_u32_e32 v1, v0, v1
	v_lshlrev_b32_e32 v3, 3, v13
	s_add_u32 s6, s8, 0x3300000
	v_ashrrev_i32_e32 v12, 6, v1
	v_and_b32_e32 v3, -16, v3
	s_addc_u32 s7, s9, 0
	v_add_u32_e32 v3, v12, v3
	v_and_b32_e32 v4, 3, v12
	s_ashr_i32 s13, s2, 31
	v_and_or_b32 v4, v3, s4, v4
	s_lshr_b32 s4, s13, 29
	s_add_i32 s4, s2, s4
	s_ashr_i32 s18, s21, 6
	s_ashr_i32 s5, s4, 3
	s_and_b32 s4, s4, -8
	s_ashr_i32 s22, s21, 8
	s_lshl_b32 s12, s18, 10
	s_sub_i32 s4, s2, s4
	s_cmp_lt_i32 s4, 0
	s_movk_i32 s33, 0xb1
	s_cselect_b32 s14, s33, 0xb0
	s_mul_i32 s4, s14, s4
	s_add_i32 s4, s4, s5
	s_mul_hi_i32 s5, s4, 0x2e8ba2e9
	s_lshr_b32 s14, s5, 31
	s_ashr_i32 s5, s5, 5
	s_add_i32 s5, s5, s14
	s_lshl_b32 s14, s5, 3
	s_mulk_i32 s5, 0xb0
	s_sub_i32 s4, s4, s5
	s_sext_i32_i16 s5, s4
	s_bfe_u32 s5, s5, 0x3001c
	s_add_i32 s5, s4, s5
	s_sext_i32_i16 s15, s5
	s_and_b32 s5, s5, 0xfff8
	s_sub_i32 s4, s4, s5
	s_sext_i32_i16 s4, s4
	v_lshrrev_b32_e32 v5, 2, v3
	v_lshlrev_b32_e32 v6, 1, v3
	v_and_b32_e32 v1, 0xc0, v1
	s_lshr_b32 s20, s15, 3
	s_add_i32 s44, s14, s4
	v_and_b32_e32 v5, 4, v5
	v_and_b32_e32 v6, 24, v6
	v_sub_u32_e32 v0, v0, v1
	s_ashr_i32 s45, s44, 31
	s_bfe_i64 s[16:17], s[20:21], 0x100000
	v_or3_b32 v4, v4, v5, v6
	v_lshlrev_b32_e32 v5, 5, v13
	v_ashrrev_i16_sdwa v0, v2, sext(v0) dst_sel:DWORD dst_unused:UNUSED_PAD src0_sel:DWORD src1_sel:BYTE_0
	s_lshl_b64 s[14:15], s[44:45], 19
	s_lshl_b64 s[16:17], s[16:17], 19
	v_and_b32_e32 v5, 32, v5
	v_bfe_i32 v14, v0, 0, 16
	s_add_u32 s46, s6, s16
	v_add_lshl_u32 v0, v5, v14, 1
	s_addc_u32 s47, s7, s17
	s_add_i32 s40, s12, 0
	v_lshl_add_u32 v132, v4, 11, v0
	s_add_i32 m0, s40, 0x10000
	v_lshl_add_u32 v134, v3, 11, v0
	global_load_lds_dwordx4 v132, s[46:47]
	s_add_i32 m0, s40, 0x12000
	s_add_u32 s16, s46, 0x40000
	global_load_lds_dwordx4 v128, s[46:47]
	s_addc_u32 s17, s47, 0
	s_add_i32 m0, s40, 0x14000
	v_mov_b32_e32 v133, 0
	global_load_lds_dwordx4 v132, s[16:17]
	s_add_i32 m0, s40, 0x16000
	s_add_u32 s48, s0, s14
	s_addc_u32 s49, s3, s15
	s_add_i32 s41, s40, 0x2000
	global_load_lds_dwordx4 v128, s[16:17]
	s_mov_b32 m0, s40
	s_add_u32 s14, s48, 0x40000
	global_load_lds_dwordx4 v134, s[48:49]
	s_mov_b32 m0, s41
	s_addc_u32 s15, s49, 0
	s_add_i32 s45, s40, 0x4000
	global_load_lds_dwordx4 v130, s[48:49]
	s_mov_b32 m0, s45
	s_add_i32 s52, s40, 0x6000
	global_load_lds_dwordx4 v134, s[14:15]
	s_mov_b32 m0, s52
	v_mov_b32_e32 v129, v133
	global_load_lds_dwordx4 v130, s[14:15]
	v_mov_b32_e32 v135, v133
	v_mov_b32_e32 v131, v133
	s_cmp_eq_u32 s22, 1
	s_mov_b32 s53, 0
	v_lshl_add_u64 v[6:7], s[46:47], 0, v[132:133]
	v_lshl_add_u64 v[4:5], s[46:47], 0, v[128:129]
	v_lshl_add_u64 v[0:1], s[48:49], 0, v[134:135]
	s_cselect_b64 s[14:15], -1, 0
	s_cmp_lg_u32 s22, 1
	v_lshl_add_u64 v[2:3], s[48:49], 0, v[130:131]
	s_cbranch_scc1 .LBB0_1582
	s_barrier
